# gMLP spatial phase: staging of V rows - all 8 row loads, gains and norms in flight together instead of one round trip per row
# speedup vs baseline: 1.0324x; 1.0017x over previous
; #define GAS __attribute__((address_space(1)))
; __device__ __forceinline__ unsigned cvt_pk_bf16(float lo, float hi) { unsigned r; asm volatile("v_cvt_pk_bf16_f32 %0, %1, %2" : "=v"(r) : "v"(lo), "v"(hi)); return r; }
; #define LAS __attribute__((address_space(3)))
; __device__ __forceinline__ void spatial_phase(LAS unsigned char* lds, const bf16_t* U, const bf16_t* V, const float* vssq, const float* vgain, const float* bsp, const bf16_t* Wsb, bf16_t* cat,
;                                               int tid, int lane, int wave) {
;     ...
;             __syncthreads();
; #pragma unroll
;             for (int i = 0; i < 8; ++i) {
;                 const int e = tid + NTHREADS * i, s = e >> 5, dc = e & 31;
;                 const u32x4 raw = *(const GAS u32x4*)(V + (size_t)(r0 + s) * 768 + g4 * 256 + dc * 8);
;                 const float rs = rv[s];
;                 const f32x4 g0 = *(const GAS f32x4*)(vgain + g4 * 256 + dc * 8), g1 = *(const GAS f32x4*)(vgain + g4 * 256 + dc * 8 + 4);
;                 u32x4 o;
;                 o.x = cvt_pk_bf16(__uint_as_float(raw.x << 16) * rs * g0[0], __uint_as_float(raw.x & 0xffff0000u) * rs * g0[1]);
;                 o.y = cvt_pk_bf16(__uint_as_float(raw.y << 16) * rs * g0[2], __uint_as_float(raw.y & 0xffff0000u) * rs * g0[3]);
;                 o.z = cvt_pk_bf16(__uint_as_float(raw.z << 16) * rs * g1[0], __uint_as_float(raw.z & 0xffff0000u) * rs * g1[1]);
;                 o.w = cvt_pk_bf16(__uint_as_float(raw.w << 16) * rs * g1[2], __uint_as_float(raw.w & 0xffff0000u) * rs * g1[3]);
;                 *(LAS u32x4*)(vS + s * 272 + dc * 8) = o;
;             }
.LBB0_1190:
	s_lshl_b32 s18, s12, 9
	s_mov_b32 s19, s39
	v_lshl_add_u64 v[2:3], v[18:19], 0, s[18:19]
	v_lshl_add_u64 v[0:1], v[2:3], 0, v[30:31]
	s_waitcnt lgkmcnt(0)
	s_barrier
	s_lshl_b32 s38, s12, 8
	v_lshl_add_u64 v[0:1], s[38:39], 2, v[20:21]
	global_load_dwordx4 v[4:7], v[0:1], off
	global_load_dwordx4 v[8:11], v[0:1], off offset:16
	v_lshl_add_u64 v[250:251], v[2:3], 0, v[30:31]
	global_load_dwordx4 v[204:207], v[250:251], off
	v_lshl_add_u64 v[250:251], v[2:3], 0, v[32:33]
	global_load_dwordx4 v[208:211], v[250:251], off
	v_lshl_add_u64 v[250:251], v[2:3], 0, v[34:35]
	global_load_dwordx4 v[212:215], v[250:251], off
	v_lshl_add_u64 v[250:251], v[2:3], 0, v[36:37]
	global_load_dwordx4 v[216:219], v[250:251], off
	v_lshl_add_u64 v[250:251], v[2:3], 0, v[38:39]
	global_load_dwordx4 v[226:229], v[250:251], off
	v_lshl_add_u64 v[250:251], v[2:3], 0, v[40:41]
	global_load_dwordx4 v[230:233], v[250:251], off
	v_lshl_add_u64 v[250:251], v[2:3], 0, v[42:43]
	global_load_dwordx4 v[234:237], v[250:251], off
	v_lshl_add_u64 v[250:251], v[2:3], 0, v[44:45]
	global_load_dwordx4 v[238:241], v[250:251], off
	ds_read_b32 v196, v73
	ds_read_b32 v197, v76
	ds_read_b32 v198, v78
	ds_read_b32 v199, v80
	ds_read_b32 v200, v82
	ds_read_b32 v201, v84
	ds_read_b32 v202, v86
	ds_read_b32 v203, v88
	s_lshl_b32 s13, s12, 2
	v_mov_b32_e32 v96, v17
	s_mov_b32 s17, 0
	s_waitcnt vmcnt(7)
	v_lshlrev_b32_e32 v242, 16, v204
	v_and_b32_e32 v243, 0xffff0000, v204
	v_lshlrev_b32_e32 v244, 16, v205
	v_and_b32_e32 v245, 0xffff0000, v205
	v_lshlrev_b32_e32 v246, 16, v206
	v_and_b32_e32 v247, 0xffff0000, v206
	v_lshlrev_b32_e32 v248, 16, v207
	v_and_b32_e32 v249, 0xffff0000, v207
	s_waitcnt lgkmcnt(0)
	v_mul_f32_e32 v242, v196, v242
	v_mul_f32_e32 v243, v196, v243
	v_mul_f32_e32 v244, v196, v244
	v_mul_f32_e32 v245, v196, v245
	v_mul_f32_e32 v246, v196, v246
	v_mul_f32_e32 v247, v196, v247
	v_mul_f32_e32 v248, v196, v248
	v_mul_f32_e32 v249, v196, v249
	v_mul_f32_e32 v242, v4, v242
	v_mul_f32_e32 v243, v5, v243
	v_mul_f32_e32 v244, v6, v244
	v_mul_f32_e32 v245, v7, v245
	v_mul_f32_e32 v246, v8, v246
	v_mul_f32_e32 v247, v9, v247
	v_mul_f32_e32 v248, v10, v248
	v_mul_f32_e32 v249, v11, v249
	v_cvt_pk_bf16_f32 v204, v242, v243
	v_cvt_pk_bf16_f32 v205, v244, v245
	v_cvt_pk_bf16_f32 v206, v246, v247
	v_cvt_pk_bf16_f32 v207, v248, v249
	ds_write_b128 v69, v[204:207]
	s_waitcnt vmcnt(6)
	v_lshlrev_b32_e32 v242, 16, v208
	v_and_b32_e32 v243, 0xffff0000, v208
	v_lshlrev_b32_e32 v244, 16, v209
	v_and_b32_e32 v245, 0xffff0000, v209
	v_lshlrev_b32_e32 v246, 16, v210
	v_and_b32_e32 v247, 0xffff0000, v210
	v_lshlrev_b32_e32 v248, 16, v211
	v_and_b32_e32 v249, 0xffff0000, v211
	v_mul_f32_e32 v242, v197, v242
	v_mul_f32_e32 v243, v197, v243
	v_mul_f32_e32 v244, v197, v244
	v_mul_f32_e32 v245, v197, v245
	v_mul_f32_e32 v246, v197, v246
	v_mul_f32_e32 v247, v197, v247
	v_mul_f32_e32 v248, v197, v248
	v_mul_f32_e32 v249, v197, v249
	v_mul_f32_e32 v242, v4, v242
	v_mul_f32_e32 v243, v5, v243
	v_mul_f32_e32 v244, v6, v244
	v_mul_f32_e32 v245, v7, v245
	v_mul_f32_e32 v246, v8, v246
	v_mul_f32_e32 v247, v9, v247
	v_mul_f32_e32 v248, v10, v248
	v_mul_f32_e32 v249, v11, v249
	v_cvt_pk_bf16_f32 v208, v242, v243
	v_cvt_pk_bf16_f32 v209, v244, v245
	v_cvt_pk_bf16_f32 v210, v246, v247
	v_cvt_pk_bf16_f32 v211, v248, v249
	ds_write_b128 v89, v[208:211]
	s_waitcnt vmcnt(5)
	v_lshlrev_b32_e32 v242, 16, v212
	v_and_b32_e32 v243, 0xffff0000, v212
	v_lshlrev_b32_e32 v244, 16, v213
	v_and_b32_e32 v245, 0xffff0000, v213
	v_lshlrev_b32_e32 v246, 16, v214
	v_and_b32_e32 v247, 0xffff0000, v214
	v_lshlrev_b32_e32 v248, 16, v215
	v_and_b32_e32 v249, 0xffff0000, v215
	v_mul_f32_e32 v242, v198, v242
	v_mul_f32_e32 v243, v198, v243
	v_mul_f32_e32 v244, v198, v244
	v_mul_f32_e32 v245, v198, v245
	v_mul_f32_e32 v246, v198, v246
	v_mul_f32_e32 v247, v198, v247
	v_mul_f32_e32 v248, v198, v248
	v_mul_f32_e32 v249, v198, v249
	v_mul_f32_e32 v242, v4, v242
	v_mul_f32_e32 v243, v5, v243
	v_mul_f32_e32 v244, v6, v244
	v_mul_f32_e32 v245, v7, v245
	v_mul_f32_e32 v246, v8, v246
	v_mul_f32_e32 v247, v9, v247
	v_mul_f32_e32 v248, v10, v248
	v_mul_f32_e32 v249, v11, v249
	v_cvt_pk_bf16_f32 v212, v242, v243
	v_cvt_pk_bf16_f32 v213, v244, v245
	v_cvt_pk_bf16_f32 v214, v246, v247
	v_cvt_pk_bf16_f32 v215, v248, v249
	ds_write_b128 v90, v[212:215]
	s_waitcnt vmcnt(4)
; #define GAS __attribute__((address_space(1)))
; __device__ __forceinline__ unsigned cvt_pk_bf16(float lo, float hi) { unsigned r; asm volatile("v_cvt_pk_bf16_f32 %0, %1, %2" : "=v"(r) : "v"(lo), "v"(hi)); return r; }
; #define LAS __attribute__((address_space(3)))
; __device__ __forceinline__ void spatial_phase(LAS unsigned char* lds, const bf16_t* U, const bf16_t* V, const float* vssq, const float* vgain, const float* bsp, const bf16_t* Wsb, bf16_t* cat,
;                                               int tid, int lane, int wave) {
;     ...
; #pragma unroll
;             for (int i = 0; i < 8; ++i) {
;                 const int e = tid + NTHREADS * i, s = e >> 5, dc = e & 31;
;                 const u32x4 raw = *(const GAS u32x4*)(V + (size_t)(r0 + s) * 768 + g4 * 256 + dc * 8);
;                 const float rs = rv[s];
;                 const f32x4 g0 = *(const GAS f32x4*)(vgain + g4 * 256 + dc * 8), g1 = *(const GAS f32x4*)(vgain + g4 * 256 + dc * 8 + 4);
;                 u32x4 o;
;                 o.x = cvt_pk_bf16(__uint_as_float(raw.x << 16) * rs * g0[0], __uint_as_float(raw.x & 0xffff0000u) * rs * g0[1]);
;                 o.y = cvt_pk_bf16(__uint_as_float(raw.y << 16) * rs * g0[2], __uint_as_float(raw.y & 0xffff0000u) * rs * g0[3]);
;                 o.z = cvt_pk_bf16(__uint_as_float(raw.z << 16) * rs * g1[0], __uint_as_float(raw.z & 0xffff0000u) * rs * g1[1]);
;                 o.w = cvt_pk_bf16(__uint_as_float(raw.w << 16) * rs * g1[2], __uint_as_float(raw.w & 0xffff0000u) * rs * g1[3]);
;                 *(LAS u32x4*)(vS + s * 272 + dc * 8) = o;
;             }
;             __syncthreads();
	v_lshlrev_b32_e32 v242, 16, v216
	v_and_b32_e32 v243, 0xffff0000, v216
	v_lshlrev_b32_e32 v244, 16, v217
	v_and_b32_e32 v245, 0xffff0000, v217
	v_lshlrev_b32_e32 v246, 16, v218
	v_and_b32_e32 v247, 0xffff0000, v218
	v_lshlrev_b32_e32 v248, 16, v219
	v_and_b32_e32 v249, 0xffff0000, v219
	v_mul_f32_e32 v242, v199, v242
	v_mul_f32_e32 v243, v199, v243
	v_mul_f32_e32 v244, v199, v244
	v_mul_f32_e32 v245, v199, v245
	v_mul_f32_e32 v246, v199, v246
	v_mul_f32_e32 v247, v199, v247
	v_mul_f32_e32 v248, v199, v248
	v_mul_f32_e32 v249, v199, v249
	v_mul_f32_e32 v242, v4, v242
	v_mul_f32_e32 v243, v5, v243
	v_mul_f32_e32 v244, v6, v244
	v_mul_f32_e32 v245, v7, v245
	v_mul_f32_e32 v246, v8, v246
	v_mul_f32_e32 v247, v9, v247
	v_mul_f32_e32 v248, v10, v248
	v_mul_f32_e32 v249, v11, v249
	v_cvt_pk_bf16_f32 v216, v242, v243
	v_cvt_pk_bf16_f32 v217, v244, v245
	v_cvt_pk_bf16_f32 v218, v246, v247
	v_cvt_pk_bf16_f32 v219, v248, v249
	ds_write_b128 v91, v[216:219]
	s_waitcnt vmcnt(3)
	v_lshlrev_b32_e32 v242, 16, v226
	v_and_b32_e32 v243, 0xffff0000, v226
	v_lshlrev_b32_e32 v244, 16, v227
	v_and_b32_e32 v245, 0xffff0000, v227
	v_lshlrev_b32_e32 v246, 16, v228
	v_and_b32_e32 v247, 0xffff0000, v228
	v_lshlrev_b32_e32 v248, 16, v229
	v_and_b32_e32 v249, 0xffff0000, v229
	v_mul_f32_e32 v242, v200, v242
	v_mul_f32_e32 v243, v200, v243
	v_mul_f32_e32 v244, v200, v244
	v_mul_f32_e32 v245, v200, v245
	v_mul_f32_e32 v246, v200, v246
	v_mul_f32_e32 v247, v200, v247
	v_mul_f32_e32 v248, v200, v248
	v_mul_f32_e32 v249, v200, v249
	v_mul_f32_e32 v242, v4, v242
	v_mul_f32_e32 v243, v5, v243
	v_mul_f32_e32 v244, v6, v244
	v_mul_f32_e32 v245, v7, v245
	v_mul_f32_e32 v246, v8, v246
	v_mul_f32_e32 v247, v9, v247
	v_mul_f32_e32 v248, v10, v248
	v_mul_f32_e32 v249, v11, v249
	v_cvt_pk_bf16_f32 v226, v242, v243
	v_cvt_pk_bf16_f32 v227, v244, v245
	v_cvt_pk_bf16_f32 v228, v246, v247
	v_cvt_pk_bf16_f32 v229, v248, v249
	ds_write_b128 v92, v[226:229]
	s_waitcnt vmcnt(2)
	v_lshlrev_b32_e32 v242, 16, v230
	v_and_b32_e32 v243, 0xffff0000, v230
	v_lshlrev_b32_e32 v244, 16, v231
	v_and_b32_e32 v245, 0xffff0000, v231
	v_lshlrev_b32_e32 v246, 16, v232
	v_and_b32_e32 v247, 0xffff0000, v232
	v_lshlrev_b32_e32 v248, 16, v233
	v_and_b32_e32 v249, 0xffff0000, v233
	v_mul_f32_e32 v242, v201, v242
	v_mul_f32_e32 v243, v201, v243
	v_mul_f32_e32 v244, v201, v244
	v_mul_f32_e32 v245, v201, v245
	v_mul_f32_e32 v246, v201, v246
	v_mul_f32_e32 v247, v201, v247
	v_mul_f32_e32 v248, v201, v248
	v_mul_f32_e32 v249, v201, v249
	v_mul_f32_e32 v242, v4, v242
	v_mul_f32_e32 v243, v5, v243
	v_mul_f32_e32 v244, v6, v244
	v_mul_f32_e32 v245, v7, v245
	v_mul_f32_e32 v246, v8, v246
	v_mul_f32_e32 v247, v9, v247
	v_mul_f32_e32 v248, v10, v248
	v_mul_f32_e32 v249, v11, v249
	v_cvt_pk_bf16_f32 v230, v242, v243
	v_cvt_pk_bf16_f32 v231, v244, v245
	v_cvt_pk_bf16_f32 v232, v246, v247
	v_cvt_pk_bf16_f32 v233, v248, v249
	ds_write_b128 v93, v[230:233]
	s_waitcnt vmcnt(1)
	v_lshlrev_b32_e32 v242, 16, v234
	v_and_b32_e32 v243, 0xffff0000, v234
	v_lshlrev_b32_e32 v244, 16, v235
	v_and_b32_e32 v245, 0xffff0000, v235
	v_lshlrev_b32_e32 v246, 16, v236
	v_and_b32_e32 v247, 0xffff0000, v236
	v_lshlrev_b32_e32 v248, 16, v237
	v_and_b32_e32 v249, 0xffff0000, v237
	v_mul_f32_e32 v242, v202, v242
	v_mul_f32_e32 v243, v202, v243
	v_mul_f32_e32 v244, v202, v244
	v_mul_f32_e32 v245, v202, v245
	v_mul_f32_e32 v246, v202, v246
	v_mul_f32_e32 v247, v202, v247
	v_mul_f32_e32 v248, v202, v248
	v_mul_f32_e32 v249, v202, v249
	v_mul_f32_e32 v242, v4, v242
	v_mul_f32_e32 v243, v5, v243
	v_mul_f32_e32 v244, v6, v244
	v_mul_f32_e32 v245, v7, v245
	v_mul_f32_e32 v246, v8, v246
	v_mul_f32_e32 v247, v9, v247
	v_mul_f32_e32 v248, v10, v248
	v_mul_f32_e32 v249, v11, v249
	v_cvt_pk_bf16_f32 v234, v242, v243
	v_cvt_pk_bf16_f32 v235, v244, v245
	v_cvt_pk_bf16_f32 v236, v246, v247
	v_cvt_pk_bf16_f32 v237, v248, v249
	ds_write_b128 v94, v[234:237]
	s_waitcnt vmcnt(0)
	v_lshlrev_b32_e32 v242, 16, v238
	v_and_b32_e32 v243, 0xffff0000, v238
	v_lshlrev_b32_e32 v244, 16, v239
	v_and_b32_e32 v245, 0xffff0000, v239
	v_lshlrev_b32_e32 v246, 16, v240
	v_and_b32_e32 v247, 0xffff0000, v240
	v_lshlrev_b32_e32 v248, 16, v241
	v_and_b32_e32 v249, 0xffff0000, v241
	v_mul_f32_e32 v242, v203, v242
	v_mul_f32_e32 v243, v203, v243
	v_mul_f32_e32 v244, v203, v244
	v_mul_f32_e32 v245, v203, v245
	v_mul_f32_e32 v246, v203, v246
	v_mul_f32_e32 v247, v203, v247
	v_mul_f32_e32 v248, v203, v248
	v_mul_f32_e32 v249, v203, v249
	v_mul_f32_e32 v242, v4, v242
	v_mul_f32_e32 v243, v5, v243
	v_mul_f32_e32 v244, v6, v244
	v_mul_f32_e32 v245, v7, v245
	v_mul_f32_e32 v246, v8, v246
	v_mul_f32_e32 v247, v9, v247
	v_mul_f32_e32 v248, v10, v248
	v_mul_f32_e32 v249, v11, v249
	v_cvt_pk_bf16_f32 v238, v242, v243
	v_cvt_pk_bf16_f32 v239, v244, v245
	v_cvt_pk_bf16_f32 v240, v246, v247
	v_cvt_pk_bf16_f32 v241, v248, v249
	ds_write_b128 v95, v[238:241]
	v_mov_b64_e32 v[50:51], v[48:49]
	s_waitcnt lgkmcnt(0)
	s_barrier
	s_branch .LBB0_1192
